# v30 + mid-point arriver per XCC issues an early non-blocking L2 writeback before the leader's release
# speedup vs baseline: 1.0388x; 1.0042x over previous
; __device__ __forceinline__ void grid_barrier(unsigned* ctr, unsigned target) {
;     asm volatile("s_waitcnt vmcnt(0)" ::: "memory");
;     __syncthreads();
;     if (threadIdx.x == 0) {
;         __threadfence();
;         asm volatile("s_waitcnt vmcnt(0)" ::: "memory");
;         __hip_atomic_fetch_add(ctr, 1u, __ATOMIC_RELAXED, __HIP_MEMORY_SCOPE_AGENT);
;         while (__hip_atomic_load(ctr, __ATOMIC_RELAXED, __HIP_MEMORY_SCOPE_AGENT) < target) __builtin_amdgcn_s_sleep(1);
;         __threadfence();
;         asm volatile("s_waitcnt vmcnt(0)" ::: "memory");
;     }
;     __syncthreads();
; }
.Lxb_follower_pre:
	v_readlane_b32 s3, v255, 15
	s_nop 0
	s_lshr_b32 s3, s3, 1
	s_sub_i32 s3, s11, s3
	v_cmp_eq_u32_e32 vcc, s3, v0
	s_cbranch_vccz .Lxb_follower
	buffer_wbl2 sc1
